# v32 + hg_cum column passes with all LDS reads in flight (hgA, hgC) + slab-0 saveB copy in one round trip
# baseline (speedup 1.0000x reference)
; __device__ __forceinline__ float sigm(float x) { return __builtin_amdgcn_rcpf(1.0f + __expf(-x)); }
; __device__ __forceinline__ void unpack8(const u32x4& w, f32x4& v0, f32x4& v1) { v0[0] = bflo(w.x); v0[1] = bfhi(w.x); v0[2] = bflo(w.y); v0[3] = bfhi(w.y); v1[0] = bflo(w.z); v1[1] = bfhi(w.z); v1[2] = bflo(w.w); v1[3] = bfhi(w.w); }
; __device__ __forceinline__ void hg_cum(const u32x4 (&ev)[2], int l, int h, const float* hlb, float* cumS, float* lbS, int tid) {
;     __syncthreads();
;     if (tid < 128) lbS[tid] = l == 0 ? 1.0f : 1.0f - sigm(hlb[512 + h * 128 + tid] - hlb[h * 128 + tid]);
;     __syncthreads();
; #pragma unroll
;     for (int q = 0; q < 2; ++q) {
;         const int idx = tid + 512 * q, t = idx >> 4, k8 = (idx & 15) * 8;
;         f32x4 a, bb; unpack8(ev[q], a, bb);
;         const f32x4 l0 = *(const f32x4*)(lbS + k8), l1 = *(const f32x4*)(lbS + k8 + 4);
; #pragma unroll
;         for (int j = 0; j < 4; ++j) { a[j] = __logf(fmaxf(1.0f - l0[j] * a[j], 1e-30f)); bb[j] = __logf(fmaxf(1.0f - l1[j] * bb[j], 1e-30f)); }
;         *(f32x4*)(cumS + t * 128 + k8) = a; *(f32x4*)(cumS + t * 128 + k8 + 4) = bb;
; __device__ __forceinline__ void hgC_item(const Bufs& B, int l, int it, unsigned char* shm, const float* hlb, const float* hn) {
;     ...
;     bf16x8 sf[4]; load_bfrag<4>(sf, B.St + (size_t)it * 16384 + wid * 16 * 128, 128, lane);
;     u32x4 ev[2], iv[2], qv[2];
; #pragma unroll
;     for (int q = 0; q < 2; ++q) { const int idx = tid + 512 * q; const bf16_t* rowp = B.bufD + (size_t)(m0 + (idx >> 4)) * 1536 + h * 128 + (idx & 15) * 8; qv[q] = *(const u32x4*)rowp; ev[q] = *(const u32x4*)(rowp + 512); iv[q] = *(const u32x4*)(rowp + 1024); }
.LBB0_824:
	s_or_b64 exec, exec, s[2:3]
	v_lshl_add_u32 v48, v65, 2, 0
	v_add_u32_e32 v69, 0x1bc00, v48
	s_waitcnt lgkmcnt(0)
	s_barrier
	v_lshlrev_b32_e32 v54, 16, v38
	v_and_b32_e32 v55, 0xffff0000, v38
	v_lshlrev_b32_e32 v50, 16, v39
	v_and_b32_e32 v51, 0xffff0000, v39
	ds_read_b128 v[58:61], v69
	ds_read_b128 v[38:41], v69 offset:16
	v_lshlrev_b32_e32 v56, 16, v36
	v_and_b32_e32 v57, 0xffff0000, v36
	v_lshlrev_b32_e32 v52, 16, v37
	s_waitcnt lgkmcnt(1)
	v_fma_f32 v36, -v58, v56, 1.0
	v_max_f32_e32 v36, 0xda24260, v36
	v_cmp_gt_f32_e32 vcc, s33, v36
	v_and_b32_e32 v53, 0xffff0000, v37
	s_waitcnt lgkmcnt(0)
	v_fma_f32 v38, -v38, v54, 1.0
	v_cndmask_b32_e64 v37, 0, 32, vcc
	v_ldexp_f32 v36, v36, v37
	v_log_f32_e32 v36, v36
	v_max_f32_e32 v38, 0xda24260, v38
	v_fma_f32 v40, -v40, v50, 1.0
	v_max_f32_e32 v40, 0xda24260, v40
	v_mul_f32_e32 v37, 0x3f317217, v36
	v_fma_f32 v37, v36, s79, -v37
	v_fmac_f32_e32 v37, 0x3377d1cf, v36
	v_fmac_f32_e32 v37, 0x3f317217, v36
	v_cmp_lt_f32_e64 s[40:41], |v36|, s80
	s_add_i32 s36, s18, s72
	s_cmpk_lt_i32 s36, 0x400
	s_cselect_b32 s36, s36, s18
	s_lshl_b32 s34, s36, 15
	s_add_u32 s38, s42, s34
	s_addc_u32 s39, s43, 0
	v_lshrrev_b32_e32 v168, 6, v179
	v_and_b32_e32 v169, 15, v179
	v_bfe_u32 v170, v179, 4, 2
	v_lshlrev_b32_e32 v168, 12, v168
	v_lshl_add_u32 v168, v169, 8, v168
	v_lshl_add_u32 v168, v170, 4, v168
	global_load_dwordx4 v[128:131], v168, s[38:39]
	global_load_dwordx4 v[132:135], v168, s[38:39] offset:64
	global_load_dwordx4 v[136:139], v168, s[38:39] offset:128
	global_load_dwordx4 v[140:143], v168, s[38:39] offset:192
	s_lshl_b32 s34, s36, 4
	s_and_b32 s34, s34, 0xfffff800
	s_lshl_b32 s35, s36, 6
	s_and_b32 s35, s35, 0x7c0
	s_or_b32 s34, s34, s35
	s_mul_i32 s34, s34, 0xc00
	s_lshl_b32 s35, s36, 3
	s_and_b32 s35, s35, 0x300
	s_add_u32 s34, s34, s35
	s_add_u32 s38, s27, s34
	s_addc_u32 s39, s29, 0
	v_lshrrev_b32_e32 v170, 4, v179
	v_mul_u32_u24_e32 v170, 0xc00, v170
	v_lshl_add_u32 v169, v169, 4, v170
	v_add_u32_e32 v170, 0x18000, v169
	global_load_dwordx4 v[144:147], v169, s[38:39]
	global_load_dwordx4 v[148:151], v169, s[38:39] offset:1024
	global_load_dwordx4 v[152:155], v169, s[38:39] offset:2048
	global_load_dwordx4 v[156:159], v170, s[38:39]
	global_load_dwordx4 v[160:163], v170, s[38:39] offset:1024
	global_load_dwordx4 v[164:167], v170, s[38:39] offset:2048
	v_lshlrev_b32_e32 v62, 16, v32
	v_and_b32_e32 v63, 0xffff0000, v32
	v_cndmask_b32_e64 v36, v36, v37, s[40:41]
	v_cndmask_b32_e32 v37, 0, v212, vcc
	v_sub_f32_e32 v36, v36, v37
	v_fma_f32 v37, -v59, v57, 1.0
	v_max_f32_e32 v37, 0xda24260, v37
	v_cmp_gt_f32_e32 vcc, s33, v37
	v_ashrrev_i32_e32 v47, 31, v46
	v_ashrrev_i32_e32 v45, 31, v44
	v_cndmask_b32_e64 v58, 0, 32, vcc
	v_ldexp_f32 v37, v37, v58
	v_log_f32_e32 v37, v37
	s_nop 0
	v_mul_f32_e32 v58, 0x3f317217, v37
	v_fma_f32 v58, v37, s79, -v58
	v_fmac_f32_e32 v58, 0x3377d1cf, v37
	v_fmac_f32_e32 v58, 0x3f317217, v37
	v_cmp_lt_f32_e64 s[40:41], |v37|, s80
	s_nop 1
	v_cndmask_b32_e64 v37, v37, v58, s[40:41]
	v_cndmask_b32_e32 v58, 0, v212, vcc
	v_cmp_gt_f32_e32 vcc, s33, v38
	v_sub_f32_e32 v37, v37, v58
	s_nop 0
	v_cndmask_b32_e64 v58, 0, 32, vcc
	v_ldexp_f32 v38, v38, v58
	v_log_f32_e32 v38, v38
	s_nop 0
	v_mul_f32_e32 v58, 0x3f317217, v38
	v_fma_f32 v58, v38, s79, -v58
	v_fmac_f32_e32 v58, 0x3377d1cf, v38
	v_fmac_f32_e32 v58, 0x3f317217, v38
	v_cmp_lt_f32_e64 s[40:41], |v38|, s80
	s_nop 1
	v_cndmask_b32_e64 v38, v38, v58, s[40:41]
	v_cndmask_b32_e32 v58, 0, v212, vcc
	v_sub_f32_e32 v58, v38, v58
	v_fma_f32 v38, -v39, v55, 1.0
	v_max_f32_e32 v38, 0xda24260, v38
	v_cmp_gt_f32_e32 vcc, s33, v38
	s_nop 1
	v_cndmask_b32_e64 v39, 0, 32, vcc
	v_ldexp_f32 v38, v38, v39
	v_log_f32_e32 v38, v38
	s_nop 0
	v_mul_f32_e32 v39, 0x3f317217, v38
	v_fma_f32 v39, v38, s79, -v39
	v_fmac_f32_e32 v39, 0x3377d1cf, v38
	v_fmac_f32_e32 v39, 0x3f317217, v38
	v_cmp_lt_f32_e64 s[40:41], |v38|, s80
	s_nop 1
	v_cndmask_b32_e64 v38, v38, v39, s[40:41]
	v_cndmask_b32_e32 v39, 0, v212, vcc
	v_sub_f32_e32 v59, v38, v39
	v_fma_f32 v38, -v60, v52, 1.0
	v_max_f32_e32 v38, 0xda24260, v38
	v_cmp_gt_f32_e32 vcc, s33, v38
	s_nop 1
	v_cndmask_b32_e64 v39, 0, 32, vcc
	v_ldexp_f32 v38, v38, v39
	v_log_f32_e32 v38, v38
	s_nop 0
	v_mul_f32_e32 v39, 0x3f317217, v38
	v_fma_f32 v39, v38, s79, -v39
	v_fmac_f32_e32 v39, 0x3377d1cf, v38
	v_fmac_f32_e32 v39, 0x3f317217, v38
	v_cmp_lt_f32_e64 s[40:41], |v38|, s80
	s_nop 1
	v_cndmask_b32_e64 v38, v38, v39, s[40:41]
	v_cndmask_b32_e32 v39, 0, v212, vcc
	v_sub_f32_e32 v38, v38, v39
	v_fma_f32 v39, -v61, v53, 1.0
	v_max_f32_e32 v39, 0xda24260, v39
	v_cmp_gt_f32_e32 vcc, s33, v39
	s_nop 1
	v_cndmask_b32_e64 v60, 0, 32, vcc
	v_ldexp_f32 v39, v39, v60
	v_log_f32_e32 v39, v39
	s_nop 0
	v_mul_f32_e32 v60, 0x3f317217, v39
	v_fma_f32 v60, v39, s79, -v60
	v_fmac_f32_e32 v60, 0x3377d1cf, v39
	v_fmac_f32_e32 v60, 0x3f317217, v39
	v_cmp_lt_f32_e64 s[40:41], |v39|, s80
	s_nop 1
	v_cndmask_b32_e64 v39, v39, v60, s[40:41]
	v_cndmask_b32_e32 v60, 0, v212, vcc
	v_cmp_gt_f32_e32 vcc, s33, v40
	v_sub_f32_e32 v39, v39, v60
	s_nop 0
	v_cndmask_b32_e64 v60, 0, 32, vcc
	v_ldexp_f32 v40, v40, v60
	v_log_f32_e32 v40, v40
	s_nop 0
	v_mul_f32_e32 v60, 0x3f317217, v40
	v_fma_f32 v60, v40, s79, -v60
	v_fmac_f32_e32 v60, 0x3377d1cf, v40
	v_fmac_f32_e32 v60, 0x3f317217, v40
	v_cmp_lt_f32_e64 s[40:41], |v40|, s80
	s_nop 1
	v_cndmask_b32_e64 v40, v40, v60, s[40:41]
	v_cndmask_b32_e32 v60, 0, v212, vcc
	v_sub_f32_e32 v60, v40, v60
	v_fma_f32 v40, -v41, v51, 1.0
	v_max_f32_e32 v40, 0xda24260, v40
	v_cmp_gt_f32_e32 vcc, s33, v40
	s_nop 1
	v_cndmask_b32_e64 v41, 0, 32, vcc
	v_ldexp_f32 v40, v40, v41
	v_log_f32_e32 v40, v40
	s_nop 0
	v_mul_f32_e32 v41, 0x3f317217, v40
	v_fma_f32 v41, v40, s79, -v41
	v_fmac_f32_e32 v41, 0x3377d1cf, v40
	v_fmac_f32_e32 v41, 0x3f317217, v40
	v_cmp_lt_f32_e64 s[40:41], |v40|, s80
	s_nop 1
	v_cndmask_b32_e64 v40, v40, v41, s[40:41]
	v_cndmask_b32_e32 v41, 0, v212, vcc
	v_sub_f32_e32 v61, v40, v41
	v_and_b32_e32 v40, 0x3fffff80, v68
	v_lshl_add_u32 v70, v40, 2, v48
	ds_write_b128 v70, v[36:39]
	ds_write_b128 v70, v[58:61] offset:16
	v_lshlrev_b32_e32 v58, 16, v33
	v_and_b32_e32 v59, 0xffff0000, v33
	v_lshlrev_b32_e32 v60, 16, v34
	v_and_b32_e32 v61, 0xffff0000, v34
	v_lshlrev_b32_e32 v40, 16, v35
	v_and_b32_e32 v41, 0xffff0000, v35
	ds_read_b128 v[36:39], v69
	ds_read_b128 v[32:35], v69 offset:16
	s_waitcnt lgkmcnt(1)
; __device__ __forceinline__ void unpack8(const u32x4& w, f32x4& v0, f32x4& v1) { v0[0] = bflo(w.x); v0[1] = bfhi(w.x); v0[2] = bflo(w.y); v0[3] = bfhi(w.y); v1[0] = bflo(w.z); v1[1] = bfhi(w.z); v1[2] = bflo(w.w); v1[3] = bfhi(w.w); }
; __device__ __forceinline__ void hg_cum(const u32x4 (&ev)[2], int l, int h, const float* hlb, float* cumS, float* lbS, int tid) {
;     ...
;         f32x4 a, bb; unpack8(ev[q], a, bb);
;         const f32x4 l0 = *(const f32x4*)(lbS + k8), l1 = *(const f32x4*)(lbS + k8 + 4);
; #pragma unroll
;         for (int j = 0; j < 4; ++j) { a[j] = __logf(fmaxf(1.0f - l0[j] * a[j], 1e-30f)); bb[j] = __logf(fmaxf(1.0f - l1[j] * bb[j], 1e-30f)); }
;         *(f32x4*)(cumS + t * 128 + k8) = a; *(f32x4*)(cumS + t * 128 + k8 + 4) = bb;
;     }
;     __syncthreads();
;     const int k = tid & 127, seg = tid >> 7;
;     { float run = 0.f;
; #pragma unroll
;       for (int tt = 0; tt < 16; ++tt) { const int t = seg * 16 + tt; run += cumS[t * 128 + k]; cumS[t * 128 + k] = run; } }
;     __syncthreads();
;     float off = 0.f;
;     for (int sp = 0; sp < seg; ++sp) off += cumS[(16 * sp + 15) * 128 + k];
	v_fma_f32 v36, -v36, v62, 1.0
	v_max_f32_e32 v36, 0xda24260, v36
	v_cmp_gt_f32_e32 vcc, s33, v36
	v_fma_f32 v37, -v37, v63, 1.0
	v_max_f32_e32 v37, 0xda24260, v37
	v_cndmask_b32_e64 v71, 0, 32, vcc
	v_ldexp_f32 v36, v36, v71
	v_log_f32_e32 v36, v36
	s_waitcnt lgkmcnt(0)
	v_fma_f32 v32, -v32, v60, 1.0
	v_max_f32_e32 v32, 0xda24260, v32
	v_fma_f32 v33, -v33, v61, 1.0
	v_mul_f32_e32 v71, 0x3f317217, v36
	v_fma_f32 v71, v36, s79, -v71
	v_fmac_f32_e32 v71, 0x3377d1cf, v36
	v_fmac_f32_e32 v71, 0x3f317217, v36
	v_cmp_lt_f32_e64 s[40:41], |v36|, s80
	v_max_f32_e32 v33, 0xda24260, v33
	v_fma_f32 v38, -v38, v58, 1.0
	v_cndmask_b32_e64 v36, v36, v71, s[40:41]
	v_cndmask_b32_e32 v71, 0, v212, vcc
	v_cmp_gt_f32_e32 vcc, s33, v37
	v_sub_f32_e32 v36, v36, v71
	v_max_f32_e32 v38, 0xda24260, v38
	v_cndmask_b32_e64 v71, 0, 32, vcc
	v_ldexp_f32 v37, v37, v71
	v_log_f32_e32 v37, v37
	v_fma_f32 v39, -v39, v59, 1.0
	v_max_f32_e32 v39, 0xda24260, v39
	v_fma_f32 v34, -v34, v40, 1.0
	v_mul_f32_e32 v71, 0x3f317217, v37
	v_fma_f32 v71, v37, s79, -v71
	v_fmac_f32_e32 v71, 0x3377d1cf, v37
	v_fmac_f32_e32 v71, 0x3f317217, v37
	v_cmp_lt_f32_e64 s[40:41], |v37|, s80
	v_max_f32_e32 v34, 0xda24260, v34
	v_fma_f32 v35, -v35, v41, 1.0
	v_cndmask_b32_e64 v37, v37, v71, s[40:41]
	v_cndmask_b32_e32 v71, 0, v212, vcc
	v_cmp_gt_f32_e32 vcc, s33, v32
	v_sub_f32_e32 v37, v37, v71
	v_max_f32_e32 v35, 0xda24260, v35
	v_cndmask_b32_e64 v71, 0, 32, vcc
	v_ldexp_f32 v32, v32, v71
	v_log_f32_e32 v32, v32
	s_nop 0
	v_mul_f32_e32 v71, 0x3f317217, v32
	v_fma_f32 v71, v32, s79, -v71
	v_fmac_f32_e32 v71, 0x3377d1cf, v32
	v_fmac_f32_e32 v71, 0x3f317217, v32
	v_cmp_lt_f32_e64 s[40:41], |v32|, s80
	s_nop 1
	v_cndmask_b32_e64 v32, v32, v71, s[40:41]
	v_cndmask_b32_e32 v71, 0, v212, vcc
	v_cmp_gt_f32_e32 vcc, s33, v33
	v_sub_f32_e32 v32, v32, v71
	s_nop 0
	v_cndmask_b32_e64 v71, 0, 32, vcc
	v_ldexp_f32 v33, v33, v71
	v_log_f32_e32 v33, v33
	s_nop 0
	v_mul_f32_e32 v71, 0x3f317217, v33
	v_fma_f32 v71, v33, s79, -v71
	v_fmac_f32_e32 v71, 0x3377d1cf, v33
	v_fmac_f32_e32 v71, 0x3f317217, v33
	v_cmp_lt_f32_e64 s[40:41], |v33|, s80
	s_nop 1
	v_cndmask_b32_e64 v33, v33, v71, s[40:41]
	v_cndmask_b32_e32 v71, 0, v212, vcc
	v_cmp_gt_f32_e32 vcc, s33, v38
	v_sub_f32_e32 v33, v33, v71
	s_nop 0
	v_cndmask_b32_e64 v71, 0, 32, vcc
	v_ldexp_f32 v38, v38, v71
	v_log_f32_e32 v38, v38
	s_nop 0
	v_mul_f32_e32 v71, 0x3f317217, v38
	v_fma_f32 v71, v38, s79, -v71
	v_fmac_f32_e32 v71, 0x3377d1cf, v38
	v_fmac_f32_e32 v71, 0x3f317217, v38
	v_cmp_lt_f32_e64 s[40:41], |v38|, s80
	s_nop 1
	v_cndmask_b32_e64 v38, v38, v71, s[40:41]
	v_cndmask_b32_e32 v71, 0, v212, vcc
	v_cmp_gt_f32_e32 vcc, s33, v39
	v_sub_f32_e32 v38, v38, v71
	s_nop 0
	v_cndmask_b32_e64 v71, 0, 32, vcc
	v_ldexp_f32 v39, v39, v71
	v_log_f32_e32 v39, v39
	s_nop 0
	v_mul_f32_e32 v71, 0x3f317217, v39
	v_fma_f32 v71, v39, s79, -v71
	v_fmac_f32_e32 v71, 0x3377d1cf, v39
	v_fmac_f32_e32 v71, 0x3f317217, v39
	v_cmp_lt_f32_e64 s[40:41], |v39|, s80
	s_nop 1
	v_cndmask_b32_e64 v39, v39, v71, s[40:41]
	v_cndmask_b32_e32 v71, 0, v212, vcc
	v_cmp_gt_f32_e32 vcc, s33, v34
	v_sub_f32_e32 v39, v39, v71
	s_nop 0
	v_cndmask_b32_e64 v71, 0, 32, vcc
	v_ldexp_f32 v34, v34, v71
	v_log_f32_e32 v34, v34
	s_nop 0
	v_mul_f32_e32 v71, 0x3f317217, v34
	v_fma_f32 v71, v34, s79, -v71
	v_fmac_f32_e32 v71, 0x3377d1cf, v34
	v_fmac_f32_e32 v71, 0x3f317217, v34
	v_cmp_lt_f32_e64 s[40:41], |v34|, s80
	s_nop 1
	v_cndmask_b32_e64 v34, v34, v71, s[40:41]
	v_cndmask_b32_e32 v71, 0, v212, vcc
	v_cmp_gt_f32_e32 vcc, s33, v35
	v_sub_f32_e32 v34, v34, v71
	s_nop 0
	v_cndmask_b32_e64 v71, 0, 32, vcc
	v_ldexp_f32 v35, v35, v71
	v_log_f32_e32 v35, v35
	s_nop 0
	v_mul_f32_e32 v71, 0x3f317217, v35
	v_fma_f32 v71, v35, s79, -v71
	v_fmac_f32_e32 v71, 0x3377d1cf, v35
	v_fmac_f32_e32 v71, 0x3f317217, v35
	v_cmp_lt_f32_e64 s[40:41], |v35|, s80
	s_nop 1
	v_cndmask_b32_e64 v35, v35, v71, s[40:41]
	v_cndmask_b32_e32 v71, 0, v212, vcc
	v_sub_f32_e32 v35, v35, v71
	ds_write_b128 v70, v[36:39] offset:16384
	ds_write_b128 v70, v[32:35] offset:16400
	v_and_b32_e32 v35, 0x7f, v67
	v_ashrrev_i32_e32 v34, 7, v67
	v_lshlrev_b32_e32 v32, 13, v34
	v_lshlrev_b32_e32 v33, 2, v35
	v_add3_u32 v32, 0, v32, v33
	s_waitcnt lgkmcnt(0)
	s_barrier
	ds_read2st64_b32 v[104:105], v32 offset1:2
	ds_read2st64_b32 v[106:107], v32 offset0:4 offset1:6
	ds_read2st64_b32 v[108:109], v32 offset0:8 offset1:10
	ds_read2st64_b32 v[110:111], v32 offset0:12 offset1:14
	ds_read2st64_b32 v[112:113], v32 offset0:16 offset1:18
	ds_read2st64_b32 v[114:115], v32 offset0:20 offset1:22
	ds_read2st64_b32 v[116:117], v32 offset0:24 offset1:26
	ds_read2st64_b32 v[118:119], v32 offset0:28 offset1:30
	v_cmp_lt_i32_e32 vcc, 0, v34
	s_waitcnt lgkmcnt(7)
	v_add_f32_e32 v104, 0, v104
	v_add_f32_e32 v105, v104, v105
	ds_write2st64_b32 v32, v104, v105 offset1:2
	s_waitcnt lgkmcnt(7)
	v_add_f32_e32 v106, v105, v106
	v_add_f32_e32 v107, v106, v107
	ds_write2st64_b32 v32, v106, v107 offset0:4 offset1:6
	s_waitcnt lgkmcnt(7)
	v_add_f32_e32 v108, v107, v108
	v_add_f32_e32 v109, v108, v109
	ds_write2st64_b32 v32, v108, v109 offset0:8 offset1:10
	s_waitcnt lgkmcnt(7)
	v_add_f32_e32 v110, v109, v110
	v_add_f32_e32 v111, v110, v111
	ds_write2st64_b32 v32, v110, v111 offset0:12 offset1:14
	s_waitcnt lgkmcnt(7)
	v_add_f32_e32 v112, v111, v112
	v_add_f32_e32 v113, v112, v113
	ds_write2st64_b32 v32, v112, v113 offset0:16 offset1:18
	s_waitcnt lgkmcnt(7)
	v_add_f32_e32 v114, v113, v114
	v_add_f32_e32 v115, v114, v115
	ds_write2st64_b32 v32, v114, v115 offset0:20 offset1:22
	s_waitcnt lgkmcnt(7)
	v_add_f32_e32 v116, v115, v116
	v_add_f32_e32 v117, v116, v117
	ds_write2st64_b32 v32, v116, v117 offset0:24 offset1:26
	s_waitcnt lgkmcnt(7)
	v_add_f32_e32 v33, v117, v118
	v_add_f32_e32 v36, v33, v119
	ds_write2st64_b32 v32, v33, v36 offset0:28 offset1:30
	v_mov_b32_e32 v33, 0
	s_waitcnt lgkmcnt(0)
	s_barrier
	s_and_saveexec_b64 s[2:3], vcc
	s_cbranch_execz .LBB0_828
	v_lshl_add_u32 v35, v35, 2, s60
	v_mov_b32_e32 v33, 0
	s_mov_b64 s[34:35], 0

; __device__ __forceinline__ u32x4 pack8(const f32x4& v0, const f32x4& v1) { u32x4 w; w.x = cvt_pk_bf16(v0[0], v0[1]); w.y = cvt_pk_bf16(v0[2], v0[3]); w.z = cvt_pk_bf16(v1[0], v1[1]); w.w = cvt_pk_bf16(v1[2], v1[3]); return w; }
; __device__ __forceinline__ void unpack8(const u32x4& w, f32x4& v0, f32x4& v1) { v0[0] = bflo(w.x); v0[1] = bfhi(w.x); v0[2] = bflo(w.y); v0[3] = bfhi(w.y); v1[0] = bflo(w.z); v1[1] = bfhi(w.z); v1[2] = bflo(w.w); v1[3] = bfhi(w.w); }
; __device__ __forceinline__ void hg_cum(const u32x4 (&ev)[2], int l, int h, const float* hlb, float* cumS, float* lbS, int tid) {
;     ...
;     float off = 0.f;
;     for (int sp = 0; sp < seg; ++sp) off += cumS[(16 * sp + 15) * 128 + k];
;     __syncthreads();
; #pragma unroll
;     for (int tt = 0; tt < 16; ++tt) cumS[(seg * 16 + tt) * 128 + k] += off;
;     __syncthreads();
; __device__ __forceinline__ void hgC_item(const Bufs& B, int l, int it, unsigned char* shm, const float* hlb, const float* hn) {
;     ...
;     for (int q = 0; q < 2; ++q) {
;         const int idx = tid + 512 * q, t = idx >> 4, k8 = (idx & 15) * 8;
;         f32x4 q0, q1, e0, e1; unpack8(qv[q], q0, q1); unpack8(ev[q], e0, e1);
;         const u32x4 iw = iv[q];
;         const int tx = t ^ (((k8 >> 3) & 7) << 3);
;         const f32x4 c0 = *(const f32x4*)(cumS + t * 128 + k8), c1 = *(const f32x4*)(cumS + t * 128 + k8 + 4), m0v = *(const f32x4*)(cumS + 31 * 128 + k8), m1v = *(const f32x4*)(cumS + 31 * 128 + k8 + 4);
;         const f32x4 l0 = *(const f32x4*)(lbS + k8), l1 = *(const f32x4*)(lbS + k8 + 4);
;         f32x4 x0, x1, y0, y1, z0, z1;
; #pragma unroll
;         for (int j = 0; j < 4; ++j) {
;             x0[j] = q0[j] * __expf(c0[j]); x1[j] = q1[j] * __expf(c1[j]);
;             y0[j] = q0[j] * __expf(fminf(c0[j] - m0v[j], 80.f)); y1[j] = q1[j] * __expf(fminf(c1[j] - m1v[j], 80.f));
;             z0[j] = l0[j] * e0[j] * __expf(fminf(m0v[j] - c0[j], 80.f)); z1[j] = l1[j] * e1[j] * __expf(fminf(m1v[j] - c1[j], 80.f));
;         }
;         *(u32x4*)(qe + t * 136 + k8) = pack8(x0, x1); *(u32x4*)(qa + t * 136 + k8) = pack8(y0, y1); *(u32x4*)(kb + t * 136 + k8) = pack8(z0, z1);
.LBB0_828:
	s_or_b64 exec, exec, s[2:3]
	s_barrier
	ds_read2st64_b32 v[104:105], v32 offset1:2
	ds_read2st64_b32 v[106:107], v32 offset0:4 offset1:6
	ds_read2st64_b32 v[108:109], v32 offset0:8 offset1:10
	ds_read2st64_b32 v[110:111], v32 offset0:12 offset1:14
	ds_read2st64_b32 v[112:113], v32 offset0:16 offset1:18
	ds_read2st64_b32 v[114:115], v32 offset0:20 offset1:22
	ds_read2st64_b32 v[116:117], v32 offset0:24 offset1:26
	ds_read2st64_b32 v[118:119], v32 offset0:28 offset1:30
	v_lshlrev_b32_e32 v38, 16, v28
	v_and_b32_e32 v39, 0xffff0000, v28
	v_lshlrev_b32_e32 v86, 16, v29
	v_and_b32_e32 v87, 0xffff0000, v29
	v_lshlrev_b32_e32 v88, 16, v30
	v_and_b32_e32 v89, 0xffff0000, v30
	v_lshlrev_b32_e32 v90, 16, v31
	v_and_b32_e32 v91, 0xffff0000, v31
	v_sub_u32_e32 v100, v48, v42
	v_cmp_gt_i32_e32 vcc, 16, v66
	s_waitcnt lgkmcnt(7)
	v_add_f32_e32 v104, v33, v104
	v_add_f32_e32 v105, v33, v105
	ds_write2st64_b32 v32, v104, v105 offset1:2
	s_waitcnt lgkmcnt(7)
	v_add_f32_e32 v106, v33, v106
	v_add_f32_e32 v107, v33, v107
	ds_write2st64_b32 v32, v106, v107 offset0:4 offset1:6
	s_waitcnt lgkmcnt(7)
	v_add_f32_e32 v108, v33, v108
	v_add_f32_e32 v109, v33, v109
	ds_write2st64_b32 v32, v108, v109 offset0:8 offset1:10
	s_waitcnt lgkmcnt(7)
	v_add_f32_e32 v110, v33, v110
	v_add_f32_e32 v111, v33, v111
	ds_write2st64_b32 v32, v110, v111 offset0:12 offset1:14
	s_waitcnt lgkmcnt(7)
	v_add_f32_e32 v112, v33, v112
	v_add_f32_e32 v113, v33, v113
	ds_write2st64_b32 v32, v112, v113 offset0:16 offset1:18
	s_waitcnt lgkmcnt(7)
	v_add_f32_e32 v114, v33, v114
	v_add_f32_e32 v115, v33, v115
	ds_write2st64_b32 v32, v114, v115 offset0:20 offset1:22
	s_waitcnt lgkmcnt(7)
	v_add_f32_e32 v116, v33, v116
	v_add_f32_e32 v117, v33, v117
	ds_write2st64_b32 v32, v116, v117 offset0:24 offset1:26
	s_waitcnt lgkmcnt(7)
	v_add_f32_e32 v34, v33, v118
	v_add_f32_e32 v33, v33, v119
	ds_write2st64_b32 v32, v34, v33 offset0:28 offset1:30
	v_lshl_add_u32 v34, v43, 9, v48
	s_waitcnt lgkmcnt(0)
	s_barrier
	ds_read_b128 v[28:31], v34
	ds_read_b128 v[34:37], v34 offset:16
	ds_read_b128 v[70:73], v48 offset:15872
	ds_read_b128 v[74:77], v48 offset:15888
	ds_read_b128 v[78:81], v69
	ds_read_b128 v[82:85], v69 offset:16
	s_waitcnt lgkmcnt(4)
	v_mul_f32_e32 v93, 0x3fb8aa3b, v34
	v_exp_f32_e32 v94, v93
	s_waitcnt lgkmcnt(3)
	v_sub_f32_e32 v93, v28, v70
	v_min_f32_e32 v93, 0x42a00000, v93
	v_mul_f32_e32 v93, 0x3fb8aa3b, v93
	v_exp_f32_e32 v96, v93
	s_waitcnt lgkmcnt(2)
	v_sub_f32_e32 v93, v34, v74
	v_min_f32_e32 v93, 0x42a00000, v93
	v_mul_f32_e32 v92, 0x3fb8aa3b, v28
	v_mul_f32_e32 v93, 0x3fb8aa3b, v93
	v_sub_f32_e32 v28, v70, v28
	v_mul_f32_e32 v70, 0x3fb8aa3b, v29
	v_exp_f32_e32 v98, v93
	v_exp_f32_e32 v93, v70
	v_mul_f32_e32 v70, 0x3fb8aa3b, v35
	v_exp_f32_e32 v95, v70
	v_sub_f32_e32 v70, v29, v71
	v_sub_f32_e32 v29, v71, v29
	v_min_f32_e32 v28, 0x42a00000, v28
	v_min_f32_e32 v29, 0x42a00000, v29
	v_mul_f32_e32 v28, 0x3fb8aa3b, v28
	v_mul_f32_e32 v29, 0x3fb8aa3b, v29
	v_exp_f32_e32 v28, v28
	v_exp_f32_e32 v29, v29
	s_waitcnt lgkmcnt(1)
	v_pk_mul_f32 v[56:57], v[78:79], v[56:57]
	v_sub_f32_e32 v34, v74, v34
	v_min_f32_e32 v34, 0x42a00000, v34
	v_pk_mul_f32 v[56:57], v[56:57], v[28:29]
	v_sub_f32_e32 v28, v75, v35
	v_min_f32_e32 v70, 0x42a00000, v70
	v_min_f32_e32 v28, 0x42a00000, v28
	v_mul_f32_e32 v34, 0x3fb8aa3b, v34
	v_mul_f32_e32 v70, 0x3fb8aa3b, v70
	v_mul_f32_e32 v28, 0x3fb8aa3b, v28
	v_exp_f32_e32 v34, v34
	v_exp_f32_e32 v97, v70
	v_sub_f32_e32 v70, v35, v75
	v_exp_f32_e32 v35, v28
	s_waitcnt lgkmcnt(0)
	v_pk_mul_f32 v[28:29], v[82:83], v[54:55]
	v_min_f32_e32 v70, 0x42a00000, v70
	v_mul_f32_e32 v70, 0x3fb8aa3b, v70
	v_pk_mul_f32 v[34:35], v[28:29], v[34:35]
	v_mul_f32_e32 v29, 0x3fb8aa3b, v36
	v_exp_f32_e32 v54, v29
	v_sub_f32_e32 v29, v30, v72
	v_min_f32_e32 v29, 0x42a00000, v29
	v_mul_f32_e32 v29, 0x3fb8aa3b, v29
	v_exp_f32_e32 v99, v70
	v_exp_f32_e32 v70, v29
	v_sub_f32_e32 v29, v36, v76
	v_min_f32_e32 v29, 0x42a00000, v29
	v_mul_f32_e32 v29, 0x3fb8aa3b, v29
	v_exp_f32_e32 v74, v29
	v_sub_f32_e32 v29, v72, v30
	v_min_f32_e32 v29, 0x42a00000, v29
	v_mul_f32_e32 v29, 0x3fb8aa3b, v29
	v_mul_f32_e32 v28, 0x3fb8aa3b, v30
	v_exp_f32_e32 v30, v29
	v_sub_f32_e32 v29, v76, v36
	v_min_f32_e32 v29, 0x42a00000, v29
	v_mul_f32_e32 v29, 0x3fb8aa3b, v29
	v_exp_f32_e32 v36, v29
	v_mul_f32_e32 v29, 0x3fb8aa3b, v31
	v_exp_f32_e32 v28, v28
	v_exp_f32_e32 v29, v29
	v_sub_f32_e32 v71, v31, v73
	v_exp_f32_e32 v92, v92
	v_mul_f32_e32 v55, 0x3fb8aa3b, v37
	v_pk_mul_f32 v[78:79], v[28:29], v[86:87]
	v_sub_f32_e32 v28, v37, v77
	v_min_f32_e32 v28, 0x42a00000, v28
	v_mul_f32_e32 v28, 0x3fb8aa3b, v28
	v_exp_f32_e32 v75, v28
	v_sub_f32_e32 v28, v73, v31
	v_min_f32_e32 v28, 0x42a00000, v28
	v_mul_f32_e32 v28, 0x3fb8aa3b, v28
	v_exp_f32_e32 v31, v28
	v_pk_mul_f32 v[28:29], v[80:81], v[52:53]
	v_min_f32_e32 v71, 0x42a00000, v71
	v_exp_f32_e32 v55, v55
	v_pk_mul_f32 v[52:53], v[28:29], v[30:31]
	v_sub_f32_e32 v28, v77, v37
	v_min_f32_e32 v28, 0x42a00000, v28
	v_mul_f32_e32 v28, 0x3fb8aa3b, v28
	v_mul_f32_e32 v71, 0x3fb8aa3b, v71
	v_exp_f32_e32 v37, v28
	v_exp_f32_e32 v71, v71
	v_pk_mul_f32 v[96:97], v[96:97], v[38:39]
	v_pk_mul_f32 v[38:39], v[92:93], v[38:39]
	v_pk_mul_f32 v[28:29], v[84:85], v[50:51]
	v_pk_mul_f32 v[92:93], v[98:99], v[88:89]
	v_pk_mul_f32 v[88:89], v[94:95], v[88:89]
	v_pk_mul_f32 v[54:55], v[54:55], v[90:91]
	v_pk_mul_f32 v[36:37], v[28:29], v[36:37]
	v_cvt_pk_bf16_f32 v28, v38, v39
	v_mul_lo_u32 v38, v43, s77
	v_pk_mul_f32 v[70:71], v[70:71], v[86:87]
	v_pk_mul_f32 v[74:75], v[74:75], v[90:91]
	v_cvt_pk_bf16_f32 v29, v78, v79
	v_cvt_pk_bf16_f32 v30, v88, v89
	v_cvt_pk_bf16_f32 v31, v54, v55
; __device__ __forceinline__ u32x4 pack8(const f32x4& v0, const f32x4& v1) { u32x4 w; w.x = cvt_pk_bf16(v0[0], v0[1]); w.y = cvt_pk_bf16(v0[2], v0[3]); w.z = cvt_pk_bf16(v1[0], v1[1]); w.w = cvt_pk_bf16(v1[2], v1[3]); return w; }
; __device__ __forceinline__ void unpack8(const u32x4& w, f32x4& v0, f32x4& v1) { v0[0] = bflo(w.x); v0[1] = bfhi(w.x); v0[2] = bflo(w.y); v0[3] = bfhi(w.y); v1[0] = bflo(w.z); v1[1] = bfhi(w.z); v1[2] = bflo(w.w); v1[3] = bfhi(w.w); }
; __device__ __forceinline__ void hgC_item(const Bufs& B, int l, int it, unsigned char* shm, const float* hlb, const float* hn) {
;     ...
;     for (int q = 0; q < 2; ++q) {
;         const int idx = tid + 512 * q, t = idx >> 4, k8 = (idx & 15) * 8;
;         f32x4 q0, q1, e0, e1; unpack8(qv[q], q0, q1); unpack8(ev[q], e0, e1);
;         const u32x4 iw = iv[q];
;         const int tx = t ^ (((k8 >> 3) & 7) << 3);
;         const f32x4 c0 = *(const f32x4*)(cumS + t * 128 + k8), c1 = *(const f32x4*)(cumS + t * 128 + k8 + 4), m0v = *(const f32x4*)(cumS + 31 * 128 + k8), m1v = *(const f32x4*)(cumS + 31 * 128 + k8 + 4);
;         const f32x4 l0 = *(const f32x4*)(lbS + k8), l1 = *(const f32x4*)(lbS + k8 + 4);
;         f32x4 x0, x1, y0, y1, z0, z1;
; #pragma unroll
;         for (int j = 0; j < 4; ++j) {
;             x0[j] = q0[j] * __expf(c0[j]); x1[j] = q1[j] * __expf(c1[j]);
;             y0[j] = q0[j] * __expf(fminf(c0[j] - m0v[j], 80.f)); y1[j] = q1[j] * __expf(fminf(c1[j] - m1v[j], 80.f));
;             z0[j] = l0[j] * e0[j] * __expf(fminf(m0v[j] - c0[j], 80.f)); z1[j] = l1[j] * e1[j] * __expf(fminf(m1v[j] - c1[j], 80.f));
;         }
;         *(u32x4*)(qe + t * 136 + k8) = pack8(x0, x1); *(u32x4*)(qa + t * 136 + k8) = pack8(y0, y1); *(u32x4*)(kb + t * 136 + k8) = pack8(z0, z1);
;         iT[(k8 + 0) * 72 + tx] = (bf16_t)(iw.x & 0xffffu); iT[(k8 + 1) * 72 + tx] = (bf16_t)(iw.x >> 16); iT[(k8 + 2) * 72 + tx] = (bf16_t)(iw.y & 0xffffu); iT[(k8 + 3) * 72 + tx] = (bf16_t)(iw.y >> 16);
;         iT[(k8 + 4) * 72 + tx] = (bf16_t)(iw.z & 0xffffu); iT[(k8 + 5) * 72 + tx] = (bf16_t)(iw.z >> 16); iT[(k8 + 6) * 72 + tx] = (bf16_t)(iw.w & 0xffffu); iT[(k8 + 7) * 72 + tx] = (bf16_t)(iw.w >> 16);
;     }
;     __syncthreads();
	v_add_u32_e32 v39, v100, v38
	v_add_u32_e32 v32, s46, v42
	v_mov_b32_e32 v33, s84
	ds_write_b128 v39, v[28:31] offset:33792
	v_cvt_pk_bf16_f32 v28, v96, v97
	v_cvt_pk_bf16_f32 v29, v70, v71
	v_cvt_pk_bf16_f32 v30, v92, v93
	v_cvt_pk_bf16_f32 v31, v74, v75
	v_mad_u32_u24 v33, v65, s76, v33
	v_bitop3_b32 v50, v68, v43, 56 bitop3:0x6c
	ds_write_b128 v39, v[28:31] offset:51200
	v_cvt_pk_bf16_f32 v28, v56, v57
	v_cvt_pk_bf16_f32 v29, v52, v53
	v_cvt_pk_bf16_f32 v30, v34, v35
	v_cvt_pk_bf16_f32 v31, v36, v37
	v_add_u32_e32 v34, v32, v38
	ds_write_b128 v34, v[28:31]
	v_lshl_add_u32 v28, v50, 1, v33
	ds_write_b16 v28, v24
	ds_write_b16_d16_hi v28, v24 offset:144
	ds_write_b16 v28, v25 offset:288
	ds_write_b16_d16_hi v28, v25 offset:432
	ds_write_b16 v28, v26 offset:576
	ds_write_b16_d16_hi v28, v26 offset:720
	ds_write_b16 v28, v27 offset:864
	ds_write_b16_d16_hi v28, v27 offset:1008
	v_lshl_add_u32 v24, v49, 9, v48
	v_lshlrev_b32_e32 v38, 16, v20
	v_and_b32_e32 v39, 0xffff0000, v20
	v_lshlrev_b32_e32 v70, 16, v21
	v_and_b32_e32 v71, 0xffff0000, v21
	v_lshlrev_b32_e32 v72, 16, v22
	v_and_b32_e32 v73, 0xffff0000, v22
	v_lshlrev_b32_e32 v74, 16, v23
	v_and_b32_e32 v75, 0xffff0000, v23
	ds_read_b128 v[20:23], v24
	ds_read_b128 v[24:27], v24 offset:16
	ds_read_b128 v[28:31], v48 offset:15872
	ds_read_b128 v[34:37], v48 offset:15888
	ds_read_b128 v[50:53], v69
	ds_read_b128 v[54:57], v69 offset:16
	s_waitcnt lgkmcnt(5)
	v_mul_f32_e32 v69, 0x3fb8aa3b, v20
	v_exp_f32_e32 v76, v69
	s_waitcnt lgkmcnt(4)
	v_mul_f32_e32 v69, 0x3fb8aa3b, v24
	v_exp_f32_e32 v78, v69
	s_waitcnt lgkmcnt(3)
	v_sub_f32_e32 v69, v20, v28
	v_sub_f32_e32 v20, v28, v20
	v_mul_f32_e32 v28, 0x3fb8aa3b, v21
	v_exp_f32_e32 v77, v28
	v_mul_f32_e32 v28, 0x3fb8aa3b, v25
	v_exp_f32_e32 v79, v28
	v_sub_f32_e32 v28, v21, v29
	v_sub_f32_e32 v21, v29, v21
	v_min_f32_e32 v20, 0x42a00000, v20
	v_min_f32_e32 v28, 0x42a00000, v28
	v_min_f32_e32 v21, 0x42a00000, v21
	v_mul_f32_e32 v20, 0x3fb8aa3b, v20
	v_mul_f32_e32 v28, 0x3fb8aa3b, v28
	v_mul_f32_e32 v21, 0x3fb8aa3b, v21
	v_exp_f32_e32 v20, v20
	v_exp_f32_e32 v81, v28
	s_waitcnt lgkmcnt(2)
	v_sub_f32_e32 v28, v25, v35
	v_exp_f32_e32 v21, v21
	v_min_f32_e32 v28, 0x42a00000, v28
	v_min_f32_e32 v69, 0x42a00000, v69
	v_mul_f32_e32 v28, 0x3fb8aa3b, v28
	v_mul_f32_e32 v69, 0x3fb8aa3b, v69
	v_exp_f32_e32 v83, v28
	s_waitcnt lgkmcnt(1)
	v_pk_mul_f32 v[28:29], v[50:51], v[62:63]
	v_exp_f32_e32 v80, v69
	v_sub_f32_e32 v69, v24, v34
	v_sub_f32_e32 v24, v34, v24
	v_pk_mul_f32 v[28:29], v[28:29], v[20:21]
	v_sub_f32_e32 v20, v35, v25
	v_min_f32_e32 v24, 0x42a00000, v24
	v_min_f32_e32 v20, 0x42a00000, v20
	v_mul_f32_e32 v24, 0x3fb8aa3b, v24
	v_mul_f32_e32 v20, 0x3fb8aa3b, v20
	v_exp_f32_e32 v24, v24
	v_exp_f32_e32 v25, v20
	s_waitcnt lgkmcnt(0)
	v_pk_mul_f32 v[20:21], v[54:55], v[60:61]
	v_min_f32_e32 v69, 0x42a00000, v69
	v_mul_f32_e32 v69, 0x3fb8aa3b, v69
	v_pk_mul_f32 v[24:25], v[20:21], v[24:25]
	v_mul_f32_e32 v21, 0x3fb8aa3b, v26
	v_exp_f32_e32 v34, v21
	v_sub_f32_e32 v21, v22, v30
	v_min_f32_e32 v21, 0x42a00000, v21
	v_mul_f32_e32 v21, 0x3fb8aa3b, v21
	v_exp_f32_e32 v50, v21
	v_sub_f32_e32 v21, v26, v36
	v_min_f32_e32 v21, 0x42a00000, v21
	v_mul_f32_e32 v21, 0x3fb8aa3b, v21
	v_exp_f32_e32 v54, v21
	v_sub_f32_e32 v21, v30, v22
	v_min_f32_e32 v21, 0x42a00000, v21
	v_mul_f32_e32 v21, 0x3fb8aa3b, v21
	v_mul_f32_e32 v20, 0x3fb8aa3b, v22
	v_exp_f32_e32 v22, v21
	v_sub_f32_e32 v21, v36, v26
	v_min_f32_e32 v21, 0x42a00000, v21
	v_mul_f32_e32 v21, 0x3fb8aa3b, v21
	v_exp_f32_e32 v26, v21
	v_mul_f32_e32 v21, 0x3fb8aa3b, v23
	v_exp_f32_e32 v20, v20
	v_exp_f32_e32 v21, v21
	v_mul_f32_e32 v30, 0x3fb8aa3b, v27
	v_exp_f32_e32 v35, v30
	v_sub_f32_e32 v30, v23, v31
	v_pk_mul_f32 v[60:61], v[20:21], v[70:71]
	v_sub_f32_e32 v20, v27, v37
	v_min_f32_e32 v20, 0x42a00000, v20
	v_mul_f32_e32 v20, 0x3fb8aa3b, v20
	v_exp_f32_e32 v55, v20
	v_sub_f32_e32 v20, v31, v23
	v_min_f32_e32 v20, 0x42a00000, v20
	v_mul_f32_e32 v20, 0x3fb8aa3b, v20
	v_exp_f32_e32 v23, v20
	v_min_f32_e32 v30, 0x42a00000, v30
	v_mul_f32_e32 v30, 0x3fb8aa3b, v30
	v_pk_mul_f32 v[20:21], v[52:53], v[58:59]
	v_exp_f32_e32 v51, v30
	v_pk_mul_f32 v[30:31], v[20:21], v[22:23]
	v_sub_f32_e32 v20, v37, v27
	v_min_f32_e32 v20, 0x42a00000, v20
	v_exp_f32_e32 v82, v69
	v_mul_f32_e32 v20, 0x3fb8aa3b, v20
	v_exp_f32_e32 v27, v20
	v_pk_mul_f32 v[34:35], v[34:35], v[74:75]
	v_pk_mul_f32 v[80:81], v[80:81], v[38:39]
	v_pk_mul_f32 v[38:39], v[76:77], v[38:39]
	v_pk_mul_f32 v[76:77], v[82:83], v[72:73]
	v_pk_mul_f32 v[72:73], v[78:79], v[72:73]
	v_pk_mul_f32 v[20:21], v[56:57], v[40:41]
	v_cvt_pk_bf16_f32 v23, v34, v35
	v_mul_lo_u32 v34, v49, s77
	v_pk_mul_f32 v[50:51], v[50:51], v[70:71]
	v_pk_mul_f32 v[54:55], v[54:55], v[74:75]
	v_pk_mul_f32 v[26:27], v[20:21], v[26:27]
	v_cvt_pk_bf16_f32 v20, v38, v39
	v_cvt_pk_bf16_f32 v21, v60, v61
	v_cvt_pk_bf16_f32 v22, v72, v73
	v_add_u32_e32 v35, v100, v34
	ds_write_b128 v35, v[20:23] offset:33792
	v_cvt_pk_bf16_f32 v20, v80, v81
	v_cvt_pk_bf16_f32 v21, v50, v51
	v_cvt_pk_bf16_f32 v22, v76, v77
	v_cvt_pk_bf16_f32 v23, v54, v55
	v_bitop3_b32 v36, v49, v68, 56 bitop3:0x78
	ds_write_b128 v35, v[20:23] offset:51200
	v_cvt_pk_bf16_f32 v20, v28, v29
	v_cvt_pk_bf16_f32 v21, v30, v31
	v_cvt_pk_bf16_f32 v22, v24, v25
	v_cvt_pk_bf16_f32 v23, v26, v27
	v_add_u32_e32 v24, v32, v34
	ds_write_b128 v24, v[20:23]
	v_lshl_add_u32 v20, v36, 1, v33
	ds_write_b16 v20, v16
	ds_write_b16_d16_hi v20, v16 offset:144
	ds_write_b16 v20, v17 offset:288
	ds_write_b16_d16_hi v20, v17 offset:432
	ds_write_b16 v20, v18 offset:576
	ds_write_b16_d16_hi v20, v18 offset:720
	ds_write_b16 v20, v19 offset:864
	ds_write_b16_d16_hi v20, v19 offset:1008
	v_lshrrev_b32_e32 v16, 2, v67
	v_and_b32_e32 v21, 15, v67
	v_and_b32_e32 v23, 12, v16
	s_waitcnt lgkmcnt(0)
	s_barrier
; __device__ __forceinline__ bf16_t f2bf(float f) { unsigned u = __float_as_uint(f); u += 0x7FFFu + ((u >> 16) & 1u); return (bf16_t)(u >> 16); }
; __device__ __forceinline__ void hgC_item(const Bufs& B, int l, int it, unsigned char* shm, const float* hlb, const float* hn) {
;     ...
;     for (int tile = wid; tile < 16; tile += 8) {
;         const int tm = tile >> 2, tn = tile & 3;
;         f32x4 acc = {0.f, 0.f, 0.f, 0.f};
;         if (tn <= tm) acc = mma_tile(qa + tm * 16 * 136, 136, kb + tn * 16 * 136, 136, 128, lane);
;         const int sc = tn * 16 + (lane & 15);
; #pragma unroll
;         for (int j = 0; j < 4; ++j) { const int t = tm * 16 + (lane >> 4) * 4 + j; P[t * 72 + sc] = f2bf(sc <= t ? acc[j] : 0.f); }
;     }
	s_mov_b64 s[2:3], exec
	v_readfirstlane_b32 s34, v66
	v_mad_u32_u24 v20, v21, s77, v176
	v_and_b32_e32 v24, 3, v66
	v_mul_u32_u24_e32 v17, 0x1100, v24
	v_lshl_or_b32 v25, v24, 4, v21
	v_add3_u32 v26, s46, v20, v17
	v_lshl_add_u32 v22, v25, 1, s47
	s_lshr_b32 s34, s34, 2
	s_mul_i32 s35, s34, 0x1100
	s_lshl_b32 s34, s34, 4
	ds_read_b128 v[80:83], v26
	ds_read_b128 v[84:87], v26 offset:64
	ds_read_b128 v[88:91], v26 offset:128
	ds_read_b128 v[92:95], v26 offset:192
	v_add_u32_e32 v27, s35, v20
	ds_read_b128 v[96:99], v27 offset:51200
	ds_read_b128 v[100:103], v27 offset:51264
	ds_read_b128 v[104:107], v27 offset:51328
	ds_read_b128 v[108:111], v27 offset:51392
	ds_read_b128 v[112:115], v27 offset:59904
	ds_read_b128 v[116:119], v27 offset:59968
	ds_read_b128 v[120:123], v27 offset:60032
	ds_read_b128 v[124:127], v27 offset:60096
	v_add_u32_e32 v72, s34, v23
	v_mad_u32_u24 v75, v72, s76, v22
	s_waitcnt lgkmcnt(3)
	v_mfma_f32_16x16x32_bf16 v[60:63], v[96:99], v[80:83], 0
	v_mfma_f32_16x16x32_bf16 v[68:71], v[112:115], v[80:83], 0
	s_waitcnt lgkmcnt(2)
	v_mfma_f32_16x16x32_bf16 v[60:63], v[100:103], v[84:87], v[60:63]
	v_mfma_f32_16x16x32_bf16 v[68:71], v[116:119], v[84:87], v[68:71]
	s_waitcnt lgkmcnt(1)
	v_mfma_f32_16x16x32_bf16 v[60:63], v[104:107], v[88:91], v[60:63]
	v_mfma_f32_16x16x32_bf16 v[68:71], v[120:123], v[88:91], v[68:71]
	s_waitcnt lgkmcnt(0)
	v_mfma_f32_16x16x32_bf16 v[60:63], v[108:111], v[92:95], v[60:63]
	v_mfma_f32_16x16x32_bf16 v[68:71], v[124:127], v[92:95], v[68:71]
	s_nop 7
	s_nop 3
	v_add_u32_e32 v73, 1, v72
	v_add_u32_e32 v74, 2, v72
	v_add_u32_e32 v76, 3, v72
	v_cmp_le_i32_e64 s[36:37], v25, v72
	v_cmp_le_i32_e64 s[38:39], v25, v73
	v_cmp_le_i32_e64 s[40:41], v25, v74
	v_cmp_le_i32_e64 vcc, v25, v76
	v_cndmask_b32_e64 v60, 0, v60, s[36:37]
	v_cndmask_b32_e64 v61, 0, v61, s[38:39]
	v_cndmask_b32_e64 v62, 0, v62, s[40:41]
	v_cndmask_b32_e64 v63, 0, v63, vcc
	v_bfe_u32 v77, v60, 16, 1
	v_bfe_u32 v73, v61, 16, 1
	v_bfe_u32 v74, v62, 16, 1
	v_bfe_u32 v76, v63, 16, 1
	v_add3_u32 v60, v60, v77, s78
	ds_write_b16_d16_hi v75, v60
	v_add3_u32 v61, v61, v73, s78
	ds_write_b16_d16_hi v75, v61 offset:144
	v_add3_u32 v62, v62, v74, s78
	ds_write_b16_d16_hi v75, v62 offset:288
	v_add3_u32 v63, v63, v76, s78
	ds_write_b16_d16_hi v75, v63 offset:432
	v_add_u32_e32 v72, 32, v72
	v_add_u32_e32 v73, 1, v72
	v_add_u32_e32 v74, 2, v72
	v_add_u32_e32 v76, 3, v72
	v_cmp_le_i32_e64 s[36:37], v25, v72
	v_cmp_le_i32_e64 s[38:39], v25, v73
	v_cmp_le_i32_e64 s[40:41], v25, v74
	v_cmp_le_i32_e64 vcc, v25, v76
	v_cndmask_b32_e64 v68, 0, v68, s[36:37]
	v_cndmask_b32_e64 v69, 0, v69, s[38:39]
	v_cndmask_b32_e64 v70, 0, v70, s[40:41]
	v_cndmask_b32_e64 v71, 0, v71, vcc
	v_bfe_u32 v77, v68, 16, 1
	v_bfe_u32 v73, v69, 16, 1
	v_bfe_u32 v74, v70, 16, 1
	v_bfe_u32 v76, v71, 16, 1
	v_add3_u32 v68, v68, v77, s78
	ds_write_b16_d16_hi v75, v68 offset:4608
	v_add3_u32 v69, v69, v73, s78
	ds_write_b16_d16_hi v75, v69 offset:4752
	v_add3_u32 v70, v70, v74, s78
	ds_write_b16_d16_hi v75, v70 offset:4896
	v_add3_u32 v71, v71, v76, s78
	ds_write_b16_d16_hi v75, v71 offset:5040
